# v36 + LRU block loop: loop-head vmcnt(0) relaxed to vmcnt(8) (previous block's 8 stores stay in flight), full drain moved to the pre-header
# speedup vs baseline: 1.0065x; 1.0000x over previous
.LBB0_863:
	s_or_b64 exec, exec, s[18:19]
	s_and_b32 s18, s21, 3
	s_ashr_i32 s27, s27, 6
	v_bfe_u32 v140, v137, 4, 2
	s_lshl_b32 s28, s18, 6
	s_lshl_b64 s[18:19], s[16:17], 23
	s_lshl_b32 s16, s27, 4
	v_lshl_or_b32 v143, v140, 2, s16
	v_lshl_or_b32 v138, s27, 2, v140
	v_ashrrev_i32_e32 v144, 3, v143
	s_movk_i32 s17, 0x90
	s_lshr_b32 s12, s22, 2
	v_mul_lo_u32 v145, v138, s17
	v_mad_u32_u24 v144, v136, s17, v144
	v_lshlrev_b32_e32 v140, 6, v140
	s_movk_i32 s17, 0x50
	s_and_b32 s12, s12, 3
	v_bitop3_b32 v149, v140, s17, 16 bitop3:0xc8
	s_movk_i32 s17, 0x60
	s_lshl_b32 s12, s12, 8
	v_bitop3_b32 v150, v140, s17, 32 bitop3:0xc8
	s_movk_i32 s17, 0x70
	v_and_b32_e32 v148, 64, v140
	v_bitop3_b32 v140, v140, s17, 48 bitop3:0xc8
	s_add_u32 s14, s14, s28
	v_add_u32_e32 v166, v144, v148
	v_add_u32_e32 v167, v149, v144
	v_add_u32_e32 v168, v150, v144
	v_add_u32_e32 v169, v140, v144
	v_add_u32_e32 v144, 0x900, v144
	v_cmp_gt_u32_e64 s[44:45], 2, v136
	s_addc_u32 s15, s15, 0
	v_and_b32_e32 v139, 63, v137
	v_add_u32_e32 v173, v140, v144
	v_cndmask_b32_e64 v140, -2, 0, s[44:45]
	v_cmp_gt_u32_e64 s[46:47], 4, v136
	s_add_u32 s12, s14, s12
	v_cmp_ne_u32_e64 s[40:41], 0, v136
	v_add_lshl_u32 v174, v140, v139, 2
	v_cndmask_b32_e64 v140, -4, 0, s[46:47]
	s_addc_u32 s17, s15, 0
	v_or_b32_e32 v163, v145, v136
	v_subbrev_co_u32_e64 v145, vcc, 0, v139, s[40:41]
	v_lshl_or_b32 v165, v139, 2, 60
	v_add_lshl_u32 v175, v140, v139, 2
	v_ashrrev_i32_e32 v139, 31, v138
	s_add_u32 s14, s12, s18
	v_or_b32_e32 v146, s24, v136
	v_add_u32_e32 v172, v150, v144
	v_lshlrev_b64 v[150:151], 1, v[138:139]
	v_lshlrev_b32_e32 v138, 15, v136
	v_mov_b32_e32 v139, v203
	s_addc_u32 s15, s17, s19
	v_or_b32_e32 v142, s16, v136
	s_movk_i32 s27, 0x110
	v_lshlrev_b32_e32 v146, 1, v146
	v_lshl_add_u64 v[152:153], s[14:15], 0, v[138:139]
	s_add_u32 s14, s12, s26
	v_mul_lo_u32 v142, v142, s27
	v_add_u32_e32 v147, 0, v146
	v_or_b32_e32 v146, 32, v146
	s_addc_u32 s15, s17, s25
	v_lshl_add_u32 v141, v136, 4, 0
	v_add_u32_e32 v142, 0, v142
	v_lshlrev_b32_e32 v164, 2, v145
	v_mul_lo_u32 v145, v162, s27
	v_mul_lo_u32 v135, v135, s27
	v_mul_lo_u32 v143, v143, s27
	v_add_u32_e32 v146, 0, v146
	v_lshlrev_b32_e32 v137, 2, v137
	v_mov_b64_e32 v[138:139], s[14:15]
	s_mov_b32 s12, 0x14000
	s_mov_b32 s16, 0
	v_cmp_eq_u32_e64 s[42:43], 0, v136
	v_add_u32_e32 v170, v144, v148
	v_add_u32_e32 v171, v149, v144
	v_cmp_gt_u32_e64 s[48:49], 8, v136
	v_and_b32_e32 v176, 0xdc, v137
	v_mad_u64_u32 v[154:155], s[14:15], v136, s12, v[138:139]
	v_mov_b32_e32 v178, 0
	v_add_u32_e32 v177, v141, v145
	v_add_u32_e32 v179, v141, v135
	v_add_u32_e32 v180, v142, v134
	v_add_u32_e32 v181, v147, v143
	v_add_u32_e32 v182, v146, v143
	s_mov_b32 s17, 0
	s_waitcnt vmcnt(0)
	s_branch .LBB0_865

.LBB0_865:
	s_waitcnt vmcnt(8)
	v_lshlrev_b32_e32 v134, 16, v110
	v_and_b32_e32 v135, 0xffff0000, v110
	v_lshlrev_b32_e32 v136, 16, v111
	v_and_b32_e32 v137, 0xffff0000, v111
	v_lshlrev_b32_e32 v184, 16, v112
	v_and_b32_e32 v185, 0xffff0000, v112
	v_lshlrev_b32_e32 v192, 16, v113
	v_and_b32_e32 v193, 0xffff0000, v113
	v_pk_fma_f32 v[134:135], v[70:71], v[134:135], v[102:103]
	v_lshlrev_b32_e32 v138, 16, v106
	v_and_b32_e32 v139, 0xffff0000, v106
	v_pk_fma_f32 v[136:137], v[72:73], v[136:137], v[104:105]
	v_lshlrev_b32_e32 v144, 16, v107
	v_and_b32_e32 v145, 0xffff0000, v107
	v_pk_fma_f32 v[184:185], v[66:67], v[184:185], v[98:99]
	v_lshlrev_b32_e32 v186, 16, v108
	v_and_b32_e32 v187, 0xffff0000, v108
	v_pk_fma_f32 v[192:193], v[68:69], v[192:193], v[100:101]
	v_lshlrev_b32_e32 v194, 16, v109
	v_and_b32_e32 v195, 0xffff0000, v109
	v_pk_fma_f32 v[134:135], v[78:79], v[138:139], v[134:135]
	v_lshlrev_b32_e32 v140, 16, v118
	v_and_b32_e32 v141, 0xffff0000, v118
	v_pk_fma_f32 v[136:137], v[80:81], v[144:145], v[136:137]
	v_lshlrev_b32_e32 v146, 16, v119
	v_and_b32_e32 v147, 0xffff0000, v119
	v_pk_fma_f32 v[184:185], v[74:75], v[186:187], v[184:185]
	v_lshlrev_b32_e32 v188, 16, v120
	v_and_b32_e32 v189, 0xffff0000, v120
	v_pk_fma_f32 v[192:193], v[76:77], v[194:195], v[192:193]
	v_lshlrev_b32_e32 v196, 16, v121
	v_and_b32_e32 v197, 0xffff0000, v121
	v_pk_fma_f32 v[134:135], v[82:83], v[140:141], v[134:135]
	v_lshlrev_b32_e32 v142, 16, v114
	v_and_b32_e32 v143, 0xffff0000, v114
	v_pk_fma_f32 v[136:137], v[84:85], v[146:147], v[136:137]
	v_lshlrev_b32_e32 v148, 16, v115
	v_and_b32_e32 v149, 0xffff0000, v115
	v_pk_fma_f32 v[184:185], v[90:91], v[188:189], v[184:185]
	v_lshlrev_b32_e32 v190, 16, v116
	v_and_b32_e32 v191, 0xffff0000, v116
	v_pk_fma_f32 v[192:193], v[92:93], v[196:197], v[192:193]
	v_lshlrev_b32_e32 v198, 16, v117
	v_and_b32_e32 v199, 0xffff0000, v117
	v_pk_fma_f32 v[134:135], v[86:87], v[142:143], v[134:135]
	v_pk_fma_f32 v[136:137], v[88:89], v[148:149], v[136:137]
	v_pk_fma_f32 v[184:185], v[94:95], v[190:191], v[184:185]
	v_pk_fma_f32 v[192:193], v[96:97], v[198:199], v[192:193]
	v_cvt_pk_bf16_f32 v134, v134, v135
	v_cvt_pk_bf16_f32 v135, v136, v137
	v_cvt_pk_bf16_f32 v136, v184, v185
	v_cvt_pk_bf16_f32 v137, v192, v193
	ds_write_b128 v177, v[134:137]
	v_pk_fma_f32 v[134:135], v[70:71], v[138:139], v[102:103]
	v_pk_fma_f32 v[136:137], v[72:73], v[144:145], v[104:105]
	v_pk_fma_f32 v[184:185], v[66:67], v[186:187], v[98:99]
	v_pk_fma_f32 v[192:193], v[68:69], v[194:195], v[100:101]
	v_pk_fma_f32 v[134:135], v[78:79], v[140:141], v[134:135]
	v_pk_fma_f32 v[136:137], v[80:81], v[146:147], v[136:137]
	v_pk_fma_f32 v[184:185], v[74:75], v[188:189], v[184:185]
	v_pk_fma_f32 v[192:193], v[76:77], v[196:197], v[192:193]
	v_pk_fma_f32 v[134:135], v[82:83], v[142:143], v[134:135]
	v_lshlrev_b32_e32 v138, 16, v126
	v_and_b32_e32 v139, 0xffff0000, v126
	v_pk_fma_f32 v[136:137], v[84:85], v[148:149], v[136:137]
	v_lshlrev_b32_e32 v144, 16, v127
	v_and_b32_e32 v145, 0xffff0000, v127
	v_pk_fma_f32 v[184:185], v[90:91], v[190:191], v[184:185]
	v_lshlrev_b32_e32 v186, 16, v128
	v_and_b32_e32 v187, 0xffff0000, v128
	v_pk_fma_f32 v[192:193], v[92:93], v[198:199], v[192:193]
	v_lshlrev_b32_e32 v194, 16, v129
	v_and_b32_e32 v195, 0xffff0000, v129
	v_pk_fma_f32 v[134:135], v[86:87], v[138:139], v[134:135]
	v_pk_fma_f32 v[136:137], v[88:89], v[144:145], v[136:137]
	v_pk_fma_f32 v[184:185], v[94:95], v[186:187], v[184:185]
	v_pk_fma_f32 v[192:193], v[96:97], v[194:195], v[192:193]
	v_cvt_pk_bf16_f32 v134, v134, v135
	v_cvt_pk_bf16_f32 v135, v136, v137
	v_cvt_pk_bf16_f32 v136, v184, v185
	v_cvt_pk_bf16_f32 v137, v192, v193
	ds_write_b128 v177, v[134:137] offset:272
	v_pk_fma_f32 v[134:135], v[70:71], v[140:141], v[102:103]
	v_pk_fma_f32 v[136:137], v[72:73], v[146:147], v[104:105]
	v_pk_fma_f32 v[184:185], v[66:67], v[188:189], v[98:99]
	v_pk_fma_f32 v[192:193], v[68:69], v[196:197], v[100:101]
	v_pk_fma_f32 v[134:135], v[78:79], v[142:143], v[134:135]
	v_pk_fma_f32 v[136:137], v[80:81], v[148:149], v[136:137]
	v_pk_fma_f32 v[184:185], v[74:75], v[190:191], v[184:185]
	v_pk_fma_f32 v[192:193], v[76:77], v[198:199], v[192:193]
	v_pk_fma_f32 v[134:135], v[82:83], v[138:139], v[134:135]
	v_lshlrev_b32_e32 v140, 16, v122
	v_and_b32_e32 v141, 0xffff0000, v122
	v_pk_fma_f32 v[136:137], v[84:85], v[144:145], v[136:137]
	v_lshlrev_b32_e32 v146, 16, v123
	v_and_b32_e32 v147, 0xffff0000, v123
	v_pk_fma_f32 v[184:185], v[90:91], v[186:187], v[184:185]
	v_lshlrev_b32_e32 v188, 16, v124
	v_and_b32_e32 v189, 0xffff0000, v124
	v_pk_fma_f32 v[192:193], v[92:93], v[194:195], v[192:193]
	v_lshlrev_b32_e32 v196, 16, v125
	v_and_b32_e32 v197, 0xffff0000, v125
	v_pk_fma_f32 v[134:135], v[86:87], v[140:141], v[134:135]
	v_pk_fma_f32 v[136:137], v[88:89], v[146:147], v[136:137]
	v_pk_fma_f32 v[184:185], v[94:95], v[188:189], v[184:185]
	v_pk_fma_f32 v[192:193], v[96:97], v[196:197], v[192:193]
	v_cvt_pk_bf16_f32 v134, v134, v135
	v_cvt_pk_bf16_f32 v135, v136, v137
	v_cvt_pk_bf16_f32 v136, v184, v185
	v_cvt_pk_bf16_f32 v137, v192, v193
	ds_write_b128 v177, v[134:137] offset:544
	v_pk_fma_f32 v[134:135], v[70:71], v[142:143], v[102:103]
	v_lshlrev_b32_e32 v136, 16, v130
	v_pk_fma_f32 v[134:135], v[78:79], v[138:139], v[134:135]
	v_and_b32_e32 v137, 0xffff0000, v130
	v_pk_fma_f32 v[134:135], v[82:83], v[140:141], v[134:135]
	v_lshlrev_b32_e32 v138, 16, v131
	v_pk_fma_f32 v[134:135], v[86:87], v[136:137], v[134:135]
	v_pk_fma_f32 v[136:137], v[72:73], v[148:149], v[104:105]
	v_and_b32_e32 v139, 0xffff0000, v131
	v_pk_fma_f32 v[136:137], v[80:81], v[144:145], v[136:137]
	v_lshlrev_b32_e32 v140, 16, v132
	v_pk_fma_f32 v[136:137], v[84:85], v[146:147], v[136:137]
	v_and_b32_e32 v141, 0xffff0000, v132
	v_pk_fma_f32 v[136:137], v[88:89], v[138:139], v[136:137]
	v_pk_fma_f32 v[138:139], v[66:67], v[190:191], v[98:99]
	v_lshlrev_b32_e32 v142, 16, v133
	v_pk_fma_f32 v[138:139], v[74:75], v[186:187], v[138:139]
	v_and_b32_e32 v143, 0xffff0000, v133
	v_pk_fma_f32 v[138:139], v[90:91], v[188:189], v[138:139]
	v_cvt_pk_bf16_f32 v134, v134, v135
	v_pk_fma_f32 v[138:139], v[94:95], v[140:141], v[138:139]
	v_pk_fma_f32 v[140:141], v[68:69], v[198:199], v[100:101]
	v_cvt_pk_bf16_f32 v135, v136, v137
	v_pk_fma_f32 v[140:141], v[76:77], v[194:195], v[140:141]
	v_cvt_pk_bf16_f32 v136, v138, v139
	v_pk_fma_f32 v[140:141], v[92:93], v[196:197], v[140:141]
	s_cmpk_eq_i32 s17, 0x780
	v_pk_fma_f32 v[140:141], v[96:97], v[142:143], v[140:141]
	s_nop 0
	v_cvt_pk_bf16_f32 v137, v140, v141
	ds_write_b128 v179, v[134:137]
	s_cbranch_scc1 .LBB0_867
	v_add_u32_e32 v132, s17, v162
	v_add_u32_e32 v106, 0x7d, v132
	v_mov_b64_e32 v[130:131], s[10:11]
	v_mad_i64_i32 v[106:107], s[14:15], v106, s3, v[130:131]
	s_lshl_b32 s12, s23, 1
	v_lshl_add_u64 v[106:107], v[106:107], 0, s[12:13]
	v_add_u32_e32 v108, 0x7e, v132
	v_lshl_add_u64 v[106:107], v[106:107], 0, v[202:203]
	v_mad_i64_i32 v[108:109], s[14:15], v108, s3, v[130:131]
	v_add_co_u32_e32 v106, vcc, 0x2000, v106
	v_lshl_add_u64 v[108:109], v[108:109], 0, s[12:13]
	v_add_u32_e32 v114, 0x7f, v132
	v_addc_co_u32_e32 v107, vcc, 0, v107, vcc
	v_lshl_add_u64 v[108:109], v[108:109], 0, v[202:203]
	v_mad_i64_i32 v[114:115], s[14:15], v114, s3, v[130:131]
	v_add_co_u32_e32 v108, vcc, 0x2000, v108
	v_lshl_add_u64 v[114:115], v[114:115], 0, s[12:13]
	v_add_u32_e32 v116, 0x80, v132
	v_addc_co_u32_e32 v109, vcc, 0, v109, vcc
	v_lshl_add_u64 v[114:115], v[114:115], 0, v[202:203]
	v_mad_i64_i32 v[116:117], s[14:15], v116, s3, v[130:131]
	v_add_co_u32_e32 v114, vcc, 0x2000, v114
	v_lshl_add_u64 v[116:117], v[116:117], 0, s[12:13]
	v_add_u32_e32 v122, 0x81, v132
	v_addc_co_u32_e32 v115, vcc, 0, v115, vcc
	v_lshl_add_u64 v[116:117], v[116:117], 0, v[202:203]
	v_mad_i64_i32 v[122:123], s[14:15], v122, s3, v[130:131]
	v_add_co_u32_e32 v116, vcc, 0x2000, v116
	v_lshl_add_u64 v[122:123], v[122:123], 0, s[12:13]
	v_add_u32_e32 v124, 0x82, v132
	v_addc_co_u32_e32 v117, vcc, 0, v117, vcc
	v_lshl_add_u64 v[122:123], v[122:123], 0, v[202:203]
	v_mad_i64_i32 v[124:125], s[14:15], v124, s3, v[130:131]
	v_add_co_u32_e32 v122, vcc, 0x2000, v122
	v_lshl_add_u64 v[124:125], v[124:125], 0, s[12:13]
	v_add_u32_e32 v132, 0x83, v132
	v_addc_co_u32_e32 v123, vcc, 0, v123, vcc
	v_lshl_add_u64 v[124:125], v[124:125], 0, v[202:203]
	v_mad_i64_i32 v[130:131], s[14:15], v132, s3, v[130:131]
	v_add_co_u32_e32 v124, vcc, 0x2000, v124
	v_lshl_add_u64 v[130:131], v[130:131], 0, s[12:13]
	s_nop 0
	v_addc_co_u32_e32 v125, vcc, 0, v125, vcc
	v_lshl_add_u64 v[130:131], v[130:131], 0, v[202:203]
	v_add_co_u32_e32 v130, vcc, 0x2000, v130
	global_load_dwordx4 v[110:113], v[106:107], off
	s_nop 0
	global_load_dwordx4 v[106:109], v[108:109], off
	v_addc_co_u32_e32 v131, vcc, 0, v131, vcc
	global_load_dwordx4 v[118:121], v[114:115], off
	s_nop 0
	global_load_dwordx4 v[114:117], v[116:117], off
	s_nop 0
	global_load_dwordx4 v[126:129], v[122:123], off
	s_nop 0
	global_load_dwordx4 v[122:125], v[124:125], off
	s_nop 0
	global_load_dwordx4 v[130:133], v[130:131], off
